# lever 8: P.V section of both SWA head loops software-pipelined (V fragments of a d-tile in flight together, Pw fragments through a 3-quad ring, counted lgkmcnt waits)
# baseline (speedup 1.0000x reference)
; #define MFMA16(a, b, c) __builtin_amdgcn_mfma_f32_16x16x32_bf16((a), (b), (c), 0, 0, 0)
; #define LBAR() do { asm volatile("s_waitcnt lgkmcnt(0)" ::: "memory"); __builtin_amdgcn_s_barrier(); asm volatile("" ::: "memory"); } while (0)
; __device__ __forceinline__ void swa_compute(SwaRaw& R, int b, int kvh, int nb, const bf16_t* P, const float* __restrict__ qg, const float* __restrict__ kg, const float* __restrict__ sinks, bf16_t* OB, LAS unsigned char* lds, int tid) {
;     ...
;         LBAR();
;         f32x4 s[10];
; #pragma unroll
;         for (int j = 0; j < 10; ++j) { f32x4 acc = {0.f, 0.f, 0.f, 0.f};
; #pragma unroll
;             for (int ks = 0; ks < 2; ++ks) acc = MFMA16(ldfrag(Ks, 72, (kt0 + j) * 16 + fr, ks * 32 + 8 * fq), ldfrag(Qs, 72, wid * 16 + fr, ks * 32 + 8 * fq), acc);
;             s[j] = acc; }
;         const int qi = wid * 16 + fr; const float sink = sinks[hq]; float m = sink;
; #pragma unroll
;         for (int j = 0; j < 10; ++j)
; #pragma unroll
;             for (int r = 0; r < 4; ++r) { const int ki = (kt0 + j) * 16 + 4 * fq + r; const bool valid = (ki > qi) && (ki <= qi + 128) && ((nb > 0) || (ki >= 128));
;                 s[j][r] = valid ? s[j][r] : -INFINITY; m = fmaxf(m, s[j][r]); }
;         m = fmaxf(m, __shfl_xor(m, 16)); m = fmaxf(m, __shfl_xor(m, 32));
.LBB0_405:
	s_waitcnt lgkmcnt(0)
	s_barrier
	s_load_dword s99, s[2:3], 0x0
	ds_read_b128 v[16:19], v67 offset:18432
	ds_read_b128 v[80:83], v68
	ds_read_b128 v[20:23], v67 offset:18496
	ds_read_b128 v[84:87], v68 offset:64
	s_waitcnt lgkmcnt(2)
	v_mfma_f32_16x16x32_bf16 v[16:19], v[16:19], v[80:83], 0
	s_waitcnt lgkmcnt(0)
	v_mfma_f32_16x16x32_bf16 v[52:55], v[20:23], v[84:87], v[16:19]
	ds_read_b128 v[20:23], v69 offset:18496
	s_nop 4
	ds_read_b128 v[16:19], v69 offset:18432
	s_waitcnt lgkmcnt(0)
	v_mfma_f32_16x16x32_bf16 v[16:19], v[16:19], v[80:83], 0
	v_cndmask_b32_e64 v52, v201, v52, s[4:5]
	v_cndmask_b32_e64 v53, v201, v53, s[6:7]
	v_cndmask_b32_e64 v54, v201, v54, s[8:9]
	v_mfma_f32_16x16x32_bf16 v[48:51], v[20:23], v[84:87], v[16:19]
	ds_read_b128 v[20:23], v70 offset:18496
	v_cndmask_b32_e64 v55, v201, v55, s[10:11]
	s_nop 1
	ds_read_b128 v[16:19], v70 offset:18432
	s_waitcnt lgkmcnt(0)
	v_mfma_f32_16x16x32_bf16 v[16:19], v[16:19], v[80:83], 0
	s_nop 0
	v_cndmask_b32_e64 v48, v201, v48, s[12:13]
	v_cndmask_b32_e64 v49, v201, v49, s[14:15]
	v_cndmask_b32_e64 v50, v201, v50, s[16:17]
	v_mfma_f32_16x16x32_bf16 v[44:47], v[20:23], v[84:87], v[16:19]
	ds_read_b128 v[20:23], v71 offset:18496
	v_cndmask_b32_e64 v51, v201, v51, s[18:19]
	s_nop 0
	ds_read_b128 v[16:19], v71 offset:18432
	s_waitcnt lgkmcnt(0)
	v_mfma_f32_16x16x32_bf16 v[16:19], v[16:19], v[80:83], 0
	s_nop 1
	v_cndmask_b32_e64 v44, v201, v44, s[20:21]
	v_cndmask_b32_e64 v45, v201, v45, s[22:23]
	v_cndmask_b32_e64 v46, v201, v46, s[24:25]
	v_mfma_f32_16x16x32_bf16 v[40:43], v[20:23], v[84:87], v[16:19]
	ds_read_b128 v[20:23], v72 offset:18496
	v_cndmask_b32_e64 v47, v201, v47, s[26:27]
	s_nop 0
	ds_read_b128 v[16:19], v72 offset:18432
	s_waitcnt lgkmcnt(0)
	v_mfma_f32_16x16x32_bf16 v[16:19], v[16:19], v[80:83], 0
	s_nop 1
	v_cndmask_b32_e64 v40, v201, v40, s[28:29]
	v_cndmask_b32_e64 v41, v201, v41, s[30:31]
	v_cndmask_b32_e64 v42, v201, v42, s[34:35]
	v_mfma_f32_16x16x32_bf16 v[36:39], v[20:23], v[84:87], v[16:19]
	ds_read_b128 v[20:23], v73 offset:18496
	v_cndmask_b32_e64 v43, v201, v43, s[36:37]
	s_nop 0
	ds_read_b128 v[16:19], v73 offset:18432
	s_waitcnt lgkmcnt(0)
	v_mfma_f32_16x16x32_bf16 v[16:19], v[16:19], v[80:83], 0
	s_nop 1
	v_cndmask_b32_e64 v36, v201, v36, s[38:39]
	v_cndmask_b32_e64 v37, v201, v37, s[40:41]
	v_cndmask_b32_e64 v38, v201, v38, s[42:43]
	v_mfma_f32_16x16x32_bf16 v[32:35], v[20:23], v[84:87], v[16:19]
	ds_read_b128 v[20:23], v74 offset:18496
	v_cndmask_b32_e64 v39, v201, v39, s[44:45]
	s_nop 0
	ds_read_b128 v[16:19], v74 offset:18432
	s_waitcnt lgkmcnt(0)
	v_mfma_f32_16x16x32_bf16 v[16:19], v[16:19], v[80:83], 0
	s_nop 1
	v_cndmask_b32_e64 v32, v201, v32, s[46:47]
	v_cndmask_b32_e64 v33, v201, v33, s[48:49]
	v_cndmask_b32_e64 v34, v201, v34, s[50:51]
	v_mfma_f32_16x16x32_bf16 v[28:31], v[20:23], v[84:87], v[16:19]
	ds_read_b128 v[20:23], v75 offset:18496
	v_cndmask_b32_e64 v35, v201, v35, s[52:53]
	s_nop 0
	ds_read_b128 v[16:19], v75 offset:18432
	s_waitcnt lgkmcnt(0)
	v_mfma_f32_16x16x32_bf16 v[16:19], v[16:19], v[80:83], 0
	s_nop 1
	v_cndmask_b32_e64 v28, v201, v28, s[54:55]
	v_cndmask_b32_e64 v29, v201, v29, s[56:57]
	v_cndmask_b32_e64 v30, v201, v30, s[58:59]
	v_mfma_f32_16x16x32_bf16 v[24:27], v[20:23], v[84:87], v[16:19]
	ds_read_b128 v[20:23], v76 offset:18496
	v_cndmask_b32_e64 v31, v201, v31, s[60:61]
	s_nop 0
	ds_read_b128 v[16:19], v76 offset:18432
	s_waitcnt lgkmcnt(0)
	v_mfma_f32_16x16x32_bf16 v[16:19], v[16:19], v[80:83], 0
	s_nop 1
	v_cndmask_b32_e64 v24, v201, v24, s[62:63]
	v_cndmask_b32_e64 v25, v201, v25, s[64:65]
	v_cndmask_b32_e64 v26, v201, v26, s[66:67]
	v_mfma_f32_16x16x32_bf16 v[20:23], v[20:23], v[84:87], v[16:19]
	v_cndmask_b32_e64 v27, v201, v27, s[68:69]
	s_nop 1
	ds_read_b128 v[16:19], v77 offset:18432
	s_waitcnt lgkmcnt(0)
	v_mfma_f32_16x16x32_bf16 v[16:19], v[16:19], v[80:83], 0
	ds_read_b128 v[80:83], v77 offset:18496
	s_nop 0
	v_cndmask_b32_e64 v20, v201, v20, s[70:71]
	v_cndmask_b32_e64 v21, v201, v21, s[72:73]
	s_waitcnt lgkmcnt(0)
	v_mfma_f32_16x16x32_bf16 v[16:19], v[80:83], v[84:87], v[16:19]
	v_cndmask_b32_e64 v22, v201, v22, s[74:75]
	v_cndmask_b32_e64 v23, v201, v23, s[76:77]
	s_nop 4
	v_cndmask_b32_e64 v82, v201, v16, s[78:79]
	v_cndmask_b32_e64 v17, v201, v17, s[80:81]
	v_cndmask_b32_e64 v83, v201, v19, s[84:85]
	s_waitcnt lgkmcnt(0)
	v_mov_b32_e32 v80, s99
	v_max3_f32 v81, v80, v52, v53
	v_max3_f32 v81, v81, v54, v55
	v_max3_f32 v81, v81, v48, v49
	v_max3_f32 v81, v81, v50, v51
	v_max3_f32 v81, v81, v44, v45
	v_max3_f32 v81, v81, v46, v47
	v_max3_f32 v81, v81, v40, v41
	v_max3_f32 v81, v81, v42, v43
	v_max3_f32 v81, v81, v36, v37
	v_max3_f32 v81, v81, v38, v39
	v_max3_f32 v81, v81, v32, v33
	v_max3_f32 v81, v81, v34, v35
	v_max3_f32 v81, v81, v28, v29
	v_max3_f32 v81, v81, v30, v31
	v_max3_f32 v81, v81, v24, v25
	v_max3_f32 v81, v81, v26, v27
	v_max3_f32 v81, v81, v20, v21
	v_max3_f32 v81, v81, v22, v23
	v_max3_f32 v16, v81, v82, v17
	v_cndmask_b32_e64 v81, v201, v18, s[82:83]
	v_max3_f32 v16, v16, v81, v83
	ds_bpermute_b32 v18, v65, v16
	s_waitcnt lgkmcnt(0)
	v_max_f32_e32 v18, v18, v18
	v_max_f32_e32 v16, v16, v18
	ds_bpermute_b32 v18, v66, v16
	s_waitcnt lgkmcnt(0)
; __device__ __forceinline__ unsigned cvt_pk_bf16(float lo, float hi) { unsigned r; asm volatile("v_cvt_pk_bf16_f32 %0, %1, %2" : "=v"(r) : "v"(lo), "v"(hi)); return r; }
; #define LAS __attribute__((address_space(3)))
; __device__ __forceinline__ void swa_compute(SwaRaw& R, int b, int kvh, int nb, const bf16_t* P, const float* __restrict__ qg, const float* __restrict__ kg, const float* __restrict__ sinks, bf16_t* OB, LAS unsigned char* lds, int tid) {
;     ...
;         float sum = 0.f;
; #pragma unroll
;         for (int j = 0; j < 10; ++j) {
; #pragma unroll
;             for (int r = 0; r < 4; ++r) { s[j][r] = __expf(s[j][r] - m); sum += s[j][r]; }
;             u32x2 w; w.x = cvt_pk_bf16(s[j][0], s[j][1]); w.y = cvt_pk_bf16(s[j][2], s[j][3]);
;             *(LAS u32x2*)(Pw + fr * 168 + j * 16 + 4 * fq) = w; }
;         sum += __shfl_xor(sum, 16); sum += __shfl_xor(sum, 32);
	v_max_f32_e32 v18, v18, v18
	v_max_f32_e32 v16, v16, v18
	v_sub_f32_e32 v18, v52, v16
	v_mul_f32_e32 v18, 0x3fb8aa3b, v18
	v_sub_f32_e32 v52, v53, v16
	v_exp_f32_e32 v18, v18
	v_mul_f32_e32 v52, 0x3fb8aa3b, v52
	v_sub_f32_e32 v53, v54, v16
	v_exp_f32_e32 v52, v52
	v_mul_f32_e32 v53, 0x3fb8aa3b, v53
	v_sub_f32_e32 v54, v55, v16
	v_exp_f32_e32 v53, v53
	v_mul_f32_e32 v54, 0x3fb8aa3b, v54
	v_exp_f32_e32 v54, v54
	v_add_f32_e32 v19, 0, v18
	v_add_f32_e32 v19, v52, v19
	v_add_f32_e32 v19, v53, v19
	v_cvt_pk_bf16_f32 v18, v18, v52
	v_add_f32_e32 v55, v54, v19
	v_cvt_pk_bf16_f32 v19, v53, v54
	ds_write_b64 v63, v[18:19]
	v_sub_f32_e32 v18, v48, v16
	v_mul_f32_e32 v18, 0x3fb8aa3b, v18
	v_sub_f32_e32 v48, v49, v16
	v_exp_f32_e32 v18, v18
	v_mul_f32_e32 v48, 0x3fb8aa3b, v48
	v_sub_f32_e32 v49, v50, v16
	v_exp_f32_e32 v48, v48
	v_mul_f32_e32 v49, 0x3fb8aa3b, v49
	v_sub_f32_e32 v50, v51, v16
	v_exp_f32_e32 v49, v49
	v_mul_f32_e32 v50, 0x3fb8aa3b, v50
	v_exp_f32_e32 v50, v50
	v_add_f32_e32 v19, v18, v55
	v_add_f32_e32 v19, v48, v19
	v_add_f32_e32 v19, v49, v19
	v_cvt_pk_bf16_f32 v18, v18, v48
	v_add_f32_e32 v51, v50, v19
	v_cvt_pk_bf16_f32 v19, v49, v50
	ds_write_b64 v63, v[18:19] offset:32
	v_sub_f32_e32 v18, v44, v16
	v_mul_f32_e32 v18, 0x3fb8aa3b, v18
	v_sub_f32_e32 v44, v45, v16
	v_exp_f32_e32 v18, v18
	v_mul_f32_e32 v44, 0x3fb8aa3b, v44
	v_sub_f32_e32 v45, v46, v16
	v_exp_f32_e32 v44, v44
	v_mul_f32_e32 v45, 0x3fb8aa3b, v45
	v_sub_f32_e32 v46, v47, v16
	v_exp_f32_e32 v45, v45
	v_mul_f32_e32 v46, 0x3fb8aa3b, v46
	v_exp_f32_e32 v46, v46
	v_add_f32_e32 v19, v18, v51
	v_add_f32_e32 v19, v44, v19
	v_add_f32_e32 v19, v45, v19
	v_cvt_pk_bf16_f32 v18, v18, v44
	v_add_f32_e32 v47, v46, v19
	v_cvt_pk_bf16_f32 v19, v45, v46
	ds_write_b64 v63, v[18:19] offset:64
	v_sub_f32_e32 v18, v40, v16
	v_mul_f32_e32 v18, 0x3fb8aa3b, v18
	v_sub_f32_e32 v40, v41, v16
	v_exp_f32_e32 v18, v18
	v_mul_f32_e32 v40, 0x3fb8aa3b, v40
	v_sub_f32_e32 v41, v42, v16
	v_exp_f32_e32 v40, v40
	v_mul_f32_e32 v41, 0x3fb8aa3b, v41
	v_sub_f32_e32 v42, v43, v16
	v_exp_f32_e32 v41, v41
	v_mul_f32_e32 v42, 0x3fb8aa3b, v42
	v_exp_f32_e32 v42, v42
	v_add_f32_e32 v19, v18, v47
	v_add_f32_e32 v19, v40, v19
	v_add_f32_e32 v19, v41, v19
	v_cvt_pk_bf16_f32 v18, v18, v40
	v_add_f32_e32 v43, v42, v19
	v_cvt_pk_bf16_f32 v19, v41, v42
	ds_write_b64 v63, v[18:19] offset:96
	v_sub_f32_e32 v18, v36, v16
	v_mul_f32_e32 v18, 0x3fb8aa3b, v18
	v_sub_f32_e32 v36, v37, v16
	v_exp_f32_e32 v18, v18
	v_mul_f32_e32 v36, 0x3fb8aa3b, v36
	v_sub_f32_e32 v37, v38, v16
	v_exp_f32_e32 v36, v36
	v_mul_f32_e32 v37, 0x3fb8aa3b, v37
	v_sub_f32_e32 v38, v39, v16
	v_exp_f32_e32 v37, v37
	v_mul_f32_e32 v38, 0x3fb8aa3b, v38
	v_exp_f32_e32 v38, v38
	v_add_f32_e32 v19, v18, v43
	v_add_f32_e32 v19, v36, v19
	v_add_f32_e32 v19, v37, v19
	v_cvt_pk_bf16_f32 v18, v18, v36
	v_add_f32_e32 v39, v38, v19
	v_cvt_pk_bf16_f32 v19, v37, v38
	ds_write_b64 v63, v[18:19] offset:128
	v_sub_f32_e32 v18, v32, v16
	v_mul_f32_e32 v18, 0x3fb8aa3b, v18
	v_sub_f32_e32 v32, v33, v16
	v_exp_f32_e32 v18, v18
	v_mul_f32_e32 v32, 0x3fb8aa3b, v32
	v_sub_f32_e32 v33, v34, v16
	v_exp_f32_e32 v32, v32
	v_mul_f32_e32 v33, 0x3fb8aa3b, v33
	v_sub_f32_e32 v34, v35, v16
	v_exp_f32_e32 v33, v33
	v_mul_f32_e32 v34, 0x3fb8aa3b, v34
	v_exp_f32_e32 v34, v34
	v_add_f32_e32 v19, v18, v39
	v_add_f32_e32 v19, v32, v19
	v_add_f32_e32 v19, v33, v19
	v_cvt_pk_bf16_f32 v18, v18, v32
	v_add_f32_e32 v35, v34, v19
	v_cvt_pk_bf16_f32 v19, v33, v34
	ds_write_b64 v63, v[18:19] offset:160
	v_sub_f32_e32 v18, v28, v16
	v_mul_f32_e32 v18, 0x3fb8aa3b, v18
	v_sub_f32_e32 v28, v29, v16
	v_exp_f32_e32 v18, v18
	v_mul_f32_e32 v28, 0x3fb8aa3b, v28
	v_sub_f32_e32 v29, v30, v16
	v_exp_f32_e32 v28, v28
	v_mul_f32_e32 v29, 0x3fb8aa3b, v29
	v_sub_f32_e32 v30, v31, v16
	v_exp_f32_e32 v29, v29
	v_mul_f32_e32 v30, 0x3fb8aa3b, v30
	v_exp_f32_e32 v30, v30
	v_add_f32_e32 v19, v18, v35
	v_add_f32_e32 v19, v28, v19
	v_add_f32_e32 v19, v29, v19
	v_cvt_pk_bf16_f32 v18, v18, v28
	v_add_f32_e32 v31, v30, v19
	v_cvt_pk_bf16_f32 v19, v29, v30
	ds_write_b64 v63, v[18:19] offset:192
	v_sub_f32_e32 v18, v24, v16
	v_mul_f32_e32 v18, 0x3fb8aa3b, v18
	v_sub_f32_e32 v24, v25, v16
	v_exp_f32_e32 v18, v18
	v_mul_f32_e32 v24, 0x3fb8aa3b, v24
	v_sub_f32_e32 v25, v26, v16
	v_exp_f32_e32 v24, v24
	v_mul_f32_e32 v25, 0x3fb8aa3b, v25
	v_sub_f32_e32 v26, v27, v16
	v_exp_f32_e32 v25, v25
	v_mul_f32_e32 v26, 0x3fb8aa3b, v26
	v_exp_f32_e32 v26, v26
	v_add_f32_e32 v19, v18, v31
	v_add_f32_e32 v19, v24, v19
	v_add_f32_e32 v19, v25, v19
	v_cvt_pk_bf16_f32 v18, v18, v24
	v_add_f32_e32 v27, v26, v19
	v_cvt_pk_bf16_f32 v19, v25, v26
	ds_write_b64 v63, v[18:19] offset:224
	v_sub_f32_e32 v18, v20, v16
	v_mul_f32_e32 v18, 0x3fb8aa3b, v18
	v_sub_f32_e32 v20, v21, v16
	v_exp_f32_e32 v18, v18
	v_mul_f32_e32 v20, 0x3fb8aa3b, v20
	v_sub_f32_e32 v21, v22, v16
	v_exp_f32_e32 v20, v20
	v_mul_f32_e32 v21, 0x3fb8aa3b, v21
	v_sub_f32_e32 v22, v23, v16
	v_exp_f32_e32 v21, v21
	v_mul_f32_e32 v22, 0x3fb8aa3b, v22
	v_exp_f32_e32 v22, v22
	v_add_f32_e32 v19, v18, v27
	v_add_f32_e32 v19, v20, v19
	v_add_f32_e32 v19, v21, v19
	v_cvt_pk_bf16_f32 v18, v18, v20
	v_add_f32_e32 v23, v22, v19
	v_cvt_pk_bf16_f32 v19, v21, v22
	ds_write_b64 v63, v[18:19] offset:256
	v_sub_f32_e32 v18, v82, v16
	v_mul_f32_e32 v18, 0x3fb8aa3b, v18
	v_sub_f32_e32 v17, v17, v16
	v_exp_f32_e32 v18, v18
	v_mul_f32_e32 v17, 0x3fb8aa3b, v17
	v_sub_f32_e32 v20, v81, v16
	v_exp_f32_e32 v17, v17
	v_mul_f32_e32 v20, 0x3fb8aa3b, v20
	v_sub_f32_e32 v21, v83, v16
	v_exp_f32_e32 v20, v20
	v_mul_f32_e32 v21, 0x3fb8aa3b, v21
	v_exp_f32_e32 v21, v21
	v_add_f32_e32 v19, v18, v23
	v_add_f32_e32 v19, v17, v19
	v_add_f32_e32 v19, v20, v19
	v_add_f32_e32 v22, v21, v19
	v_cvt_pk_bf16_f32 v18, v18, v17
	ds_bpermute_b32 v17, v65, v22
	v_cvt_pk_bf16_f32 v19, v20, v21
	ds_write_b64 v63, v[18:19] offset:288
	v_sub_f32_e32 v16, v80, v16
	v_mul_f32_e32 v16, 0x3fb8aa3b, v16
	s_waitcnt lgkmcnt(1)
; __device__ __forceinline__ unsigned cvt_pk_bf16(float lo, float hi) { unsigned r; asm volatile("v_cvt_pk_bf16_f32 %0, %1, %2" : "=v"(r) : "v"(lo), "v"(hi)); return r; }
; #define LAS __attribute__((address_space(3)))
; #define MFMA16(a, b, c) __builtin_amdgcn_mfma_f32_16x16x32_bf16((a), (b), (c), 0, 0, 0)
; __device__ __forceinline__ void swa_compute(SwaRaw& R, int b, int kvh, int nb, const bf16_t* P, const float* __restrict__ qg, const float* __restrict__ kg, const float* __restrict__ sinks, bf16_t* OB, LAS unsigned char* lds, int tid) {
;     ...
;         const float inv = 1.0f / (sum + __expf(sink - m));
;         asm volatile("s_waitcnt lgkmcnt(0)" ::: "memory"); __builtin_amdgcn_wave_barrier();
; #pragma unroll
;         for (int dt = 0; dt < 4; ++dt) { f32x4 acc = {0.f, 0.f, 0.f, 0.f};
; #pragma unroll
;             for (int ks = 0; ks < 5; ++ks) { const LAS bf16_t* vp = Vr + (kt0 * 16 + ks * 32 + 8 * fq + (fr >> 2)) * 72 + dt * 16 + 4 * (fr & 3);
;                 const v4i16_t lo = __builtin_amdgcn_ds_read_tr16_b64_v4i16((LAS v4i16_t*)vp), hi = __builtin_amdgcn_ds_read_tr16_b64_v4i16((LAS v4i16_t*)(vp + 4 * 72));
;                 const bf16x8 vf = {lo[0], lo[1], lo[2], lo[3], hi[0], hi[1], hi[2], hi[3]};
;                 acc = MFMA16(vf, ldfrag(Pw, 168, fr, ks * 32 + 8 * fq), acc); }
;             u32x2 w; w.x = cvt_pk_bf16(acc[0] * inv, acc[1] * inv); w.y = cvt_pk_bf16(acc[2] * inv, acc[3] * inv);
;             *(u32x2*)(OB + (rq0 + qi) * 1024 + hq * 64 + dt * 16 + 4 * fq) = w; }
	v_add_f32_e32 v17, v22, v17
	ds_bpermute_b32 v18, v66, v17
	v_exp_f32_e32 v16, v16
	v_add_u32_e32 v31, v193, v64
	v_add_u32_e32 v32, v63, v94
	s_waitcnt lgkmcnt(0)
	s_waitcnt lgkmcnt(0)
	v_add_f32_e32 v17, v17, v18
	v_add_f32_e32 v16, v16, v17
	v_div_scale_f32 v17, s[88:89], v16, v16, 1.0
	v_rcp_f32_e32 v18, v17
	s_nop 0
	v_fma_f32 v19, -v17, v18, 1.0
	v_fmac_f32_e32 v18, v19, v18
	v_div_scale_f32 v19, vcc, 1.0, v16, 1.0
	v_mul_f32_e32 v20, v19, v18
	v_fma_f32 v21, -v17, v20, v19
	v_fmac_f32_e32 v20, v21, v18
	v_fma_f32 v17, -v17, v20, v19
	v_div_fmas_f32 v17, v17, v18, v20
	ds_read_b64_tr_b16 v[100:101], v31 offset:55296
	ds_read_b64_tr_b16 v[102:103], v31 offset:55872
	ds_read_b128 v[22:25], v32
	ds_read_b64_tr_b16 v[104:105], v31 offset:59904
	ds_read_b64_tr_b16 v[106:107], v31 offset:60480
	ds_read_b128 v[26:29], v32 offset:64
	ds_read_b64_tr_b16 v[240:241], v31 offset:64512
	ds_read_b64_tr_b16 v[242:243], v31 offset:65088
	ds_read_b128 v[252:255], v32 offset:128
	ds_read_b64_tr_b16 v[244:245], v78 offset:55296
	ds_read_b64_tr_b16 v[246:247], v78 offset:55872
	ds_read_b64_tr_b16 v[248:249], v79 offset:55296
	ds_read_b64_tr_b16 v[250:251], v79 offset:55872
	s_waitcnt lgkmcnt(10)
	v_mfma_f32_16x16x32_bf16 v[18:21], v[100:103], v[22:25], 0
	ds_read_b128 v[22:25], v32 offset:192
	ds_read_b64_tr_b16 v[100:101], v31 offset:55328
	ds_read_b64_tr_b16 v[102:103], v31 offset:55904
	v_div_fixup_f32 v30, v17, v16, 1.0
	v_lshl_add_u64 v[16:17], v[58:59], 0, s[96:97]
	s_waitcnt lgkmcnt(10)
	v_mfma_f32_16x16x32_bf16 v[18:21], v[104:107], v[26:29], v[18:21]
	ds_read_b128 v[26:29], v32 offset:256
	ds_read_b64_tr_b16 v[104:105], v31 offset:59936
	ds_read_b64_tr_b16 v[106:107], v31 offset:60512
	s_add_u32 s96, s96, 0x80
	s_addc_u32 s97, s97, 0
	s_waitcnt lgkmcnt(10)
	v_mfma_f32_16x16x32_bf16 v[18:21], v[240:243], v[252:255], v[18:21]
	ds_read_b128 v[252:255], v32
	ds_read_b64_tr_b16 v[240:241], v31 offset:64544
	ds_read_b64_tr_b16 v[242:243], v31 offset:65120
	s_add_u32 s2, s2, 4
	s_addc_u32 s3, s3, 0
	s_waitcnt lgkmcnt(8)
	v_mfma_f32_16x16x32_bf16 v[18:21], v[244:247], v[22:25], v[18:21]
	ds_read_b128 v[22:25], v32 offset:64
	ds_read_b64_tr_b16 v[244:245], v78 offset:55328
	ds_read_b64_tr_b16 v[246:247], v78 offset:55904
	s_cmpk_lg_i32 s96, 0x200
	s_waitcnt lgkmcnt(8)
	v_mfma_f32_16x16x32_bf16 v[18:21], v[248:251], v[26:29], v[18:21]
	ds_read_b128 v[26:29], v32 offset:128
	ds_read_b64_tr_b16 v[248:249], v79 offset:55328
	ds_read_b64_tr_b16 v[250:251], v79 offset:55904
	s_nop 7
	v_mul_f32_e32 v18, v18, v30
	v_mul_f32_e32 v19, v19, v30
	v_cvt_pk_bf16_f32 v18, v18, v19
	v_mul_f32_e32 v19, v20, v30
	v_mul_f32_e32 v20, v21, v30
	v_cvt_pk_bf16_f32 v19, v19, v20
	global_store_dwordx2 v[16:17], v[18:19], off offset:-64
	s_waitcnt lgkmcnt(8)
	v_mfma_f32_16x16x32_bf16 v[18:21], v[100:103], v[252:255], 0
	ds_read_b128 v[252:255], v32 offset:192
	ds_read_b64_tr_b16 v[100:101], v31 offset:55360
	ds_read_b64_tr_b16 v[102:103], v31 offset:55936
	s_waitcnt lgkmcnt(8)
	v_mfma_f32_16x16x32_bf16 v[18:21], v[104:107], v[22:25], v[18:21]
	ds_read_b128 v[22:25], v32 offset:256
	ds_read_b64_tr_b16 v[104:105], v31 offset:59968
	ds_read_b64_tr_b16 v[106:107], v31 offset:60544
	s_waitcnt lgkmcnt(8)
	v_mfma_f32_16x16x32_bf16 v[18:21], v[240:243], v[26:29], v[18:21]
	ds_read_b128 v[26:29], v32
	ds_read_b64_tr_b16 v[240:241], v31 offset:64576
	ds_read_b64_tr_b16 v[242:243], v31 offset:65152
	s_waitcnt lgkmcnt(8)
	v_mfma_f32_16x16x32_bf16 v[18:21], v[244:247], v[252:255], v[18:21]
	ds_read_b128 v[252:255], v32 offset:64
	ds_read_b64_tr_b16 v[244:245], v78 offset:55360
	ds_read_b64_tr_b16 v[246:247], v78 offset:55936
	s_waitcnt lgkmcnt(8)
	v_mfma_f32_16x16x32_bf16 v[18:21], v[248:251], v[22:25], v[18:21]
	ds_read_b128 v[22:25], v32 offset:128
	ds_read_b64_tr_b16 v[248:249], v79 offset:55360
	ds_read_b64_tr_b16 v[250:251], v79 offset:55936
	s_nop 7
	v_mul_f32_e32 v18, v18, v30
	v_mul_f32_e32 v19, v19, v30
	v_cvt_pk_bf16_f32 v18, v18, v19
	v_mul_f32_e32 v19, v20, v30
	v_mul_f32_e32 v20, v21, v30
	v_cvt_pk_bf16_f32 v19, v19, v20
	global_store_dwordx2 v[16:17], v[18:19], off offset:-32
	s_waitcnt lgkmcnt(8)
	v_mfma_f32_16x16x32_bf16 v[18:21], v[100:103], v[26:29], 0
	ds_read_b128 v[26:29], v32 offset:192
	ds_read_b64_tr_b16 v[100:101], v31 offset:55392
	ds_read_b64_tr_b16 v[102:103], v31 offset:55968
	s_waitcnt lgkmcnt(8)
	v_mfma_f32_16x16x32_bf16 v[18:21], v[104:107], v[252:255], v[18:21]
	ds_read_b128 v[252:255], v32 offset:256
	ds_read_b64_tr_b16 v[104:105], v31 offset:60000
	ds_read_b64_tr_b16 v[106:107], v31 offset:60576
	s_waitcnt lgkmcnt(8)
	v_mfma_f32_16x16x32_bf16 v[18:21], v[240:243], v[22:25], v[18:21]
	ds_read_b128 v[22:25], v32
	ds_read_b64_tr_b16 v[240:241], v31 offset:64608
	ds_read_b64_tr_b16 v[242:243], v31 offset:65184
	s_waitcnt lgkmcnt(8)
	v_mfma_f32_16x16x32_bf16 v[18:21], v[244:247], v[26:29], v[18:21]
	ds_read_b128 v[26:29], v32 offset:64
	ds_read_b64_tr_b16 v[244:245], v78 offset:55392
	ds_read_b64_tr_b16 v[246:247], v78 offset:55968
	s_waitcnt lgkmcnt(8)
	v_mfma_f32_16x16x32_bf16 v[18:21], v[248:251], v[252:255], v[18:21]
	ds_read_b128 v[252:255], v32 offset:128
	ds_read_b64_tr_b16 v[248:249], v79 offset:55392
	ds_read_b64_tr_b16 v[250:251], v79 offset:55968
	s_nop 7
	v_mul_f32_e32 v18, v30, v18
	v_mul_f32_e32 v19, v30, v19
	v_cvt_pk_bf16_f32 v18, v18, v19
	v_mul_f32_e32 v19, v30, v20
	v_mul_f32_e32 v20, v30, v21
	v_cvt_pk_bf16_f32 v19, v19, v20
	global_store_dwordx2 v[16:17], v[18:19], off
	s_waitcnt lgkmcnt(8)
	v_mfma_f32_16x16x32_bf16 v[18:21], v[100:103], v[22:25], 0
	ds_read_b128 v[22:25], v32 offset:192
	s_waitcnt lgkmcnt(6)
	v_mfma_f32_16x16x32_bf16 v[18:21], v[104:107], v[26:29], v[18:21]
	ds_read_b128 v[26:29], v32 offset:256
	s_waitcnt lgkmcnt(4)
	v_mfma_f32_16x16x32_bf16 v[18:21], v[240:243], v[252:255], v[18:21]
	s_waitcnt lgkmcnt(1)
	v_mfma_f32_16x16x32_bf16 v[18:21], v[244:247], v[22:25], v[18:21]
	s_waitcnt lgkmcnt(0)
	v_mfma_f32_16x16x32_bf16 v[18:21], v[248:251], v[26:29], v[18:21]
	s_nop 7
	v_mul_f32_e32 v18, v30, v18
	v_mul_f32_e32 v19, v30, v19
	v_cvt_pk_bf16_f32 v18, v18, v19
	v_mul_f32_e32 v19, v30, v20
	v_mul_f32_e32 v20, v30, v21
	v_cvt_pk_bf16_f32 v19, v19, v20
	global_store_dwordx2 v[16:17], v[18:19], off offset:32
	s_waitcnt lgkmcnt(0)
	s_barrier
	s_cbranch_scc0 .LBB0_392

; #define MFMA16(a, b, c) __builtin_amdgcn_mfma_f32_16x16x32_bf16((a), (b), (c), 0, 0, 0)
; #define LBAR() do { asm volatile("s_waitcnt lgkmcnt(0)" ::: "memory"); __builtin_amdgcn_s_barrier(); asm volatile("" ::: "memory"); } while (0)
; __device__ __forceinline__ void swa_compute(SwaRaw& R, int b, int kvh, int nb, const bf16_t* P, const float* __restrict__ qg, const float* __restrict__ kg, const float* __restrict__ sinks, bf16_t* OB, LAS unsigned char* lds, int tid) {
;     ...
;         LBAR();
;         f32x4 s[10];
; #pragma unroll
;         for (int j = 0; j < 10; ++j) { f32x4 acc = {0.f, 0.f, 0.f, 0.f};
; #pragma unroll
;             for (int ks = 0; ks < 2; ++ks) acc = MFMA16(ldfrag(Ks, 72, (kt0 + j) * 16 + fr, ks * 32 + 8 * fq), ldfrag(Qs, 72, wid * 16 + fr, ks * 32 + 8 * fq), acc);
;             s[j] = acc; }
;         const int qi = wid * 16 + fr; const float sink = sinks[hq]; float m = sink;
; #pragma unroll
;         for (int j = 0; j < 10; ++j)
; #pragma unroll
;             for (int r = 0; r < 4; ++r) { const int ki = (kt0 + j) * 16 + 4 * fq + r; const bool valid = (ki > qi) && (ki <= qi + 128) && ((nb > 0) || (ki >= 128));
;                 s[j][r] = valid ? s[j][r] : -INFINITY; m = fmaxf(m, s[j][r]); }
;         m = fmaxf(m, __shfl_xor(m, 16)); m = fmaxf(m, __shfl_xor(m, 32));
.LBB0_498:
	s_waitcnt lgkmcnt(0)
	s_barrier
	s_load_dword s99, s[2:3], 0x0
	ds_read_b128 v[18:21], v0 offset:18432
	ds_read_b128 v[82:85], v67
	ds_read_b128 v[22:25], v0 offset:18496
	ds_read_b128 v[122:125], v67 offset:64
	s_waitcnt lgkmcnt(2)
	v_mfma_f32_16x16x32_bf16 v[18:21], v[18:21], v[82:85], 0
	s_waitcnt lgkmcnt(0)
	v_mfma_f32_16x16x32_bf16 v[54:57], v[22:25], v[122:125], v[18:21]
	ds_read_b128 v[22:25], v68 offset:18496
	s_nop 4
	ds_read_b128 v[18:21], v68 offset:18432
	s_waitcnt lgkmcnt(0)
	v_mfma_f32_16x16x32_bf16 v[18:21], v[18:21], v[82:85], 0
	v_cndmask_b32_e64 v54, v177, v54, s[4:5]
	v_cndmask_b32_e64 v55, v177, v55, s[6:7]
	v_cndmask_b32_e64 v56, v177, v56, s[8:9]
	v_mfma_f32_16x16x32_bf16 v[50:53], v[22:25], v[122:125], v[18:21]
	ds_read_b128 v[22:25], v69 offset:18496
	v_cndmask_b32_e64 v57, v177, v57, s[10:11]
	s_nop 1
	ds_read_b128 v[18:21], v69 offset:18432
	s_waitcnt lgkmcnt(0)
	v_mfma_f32_16x16x32_bf16 v[18:21], v[18:21], v[82:85], 0
	s_nop 0
	v_cndmask_b32_e64 v50, v177, v50, s[12:13]
	v_cndmask_b32_e64 v51, v177, v51, s[14:15]
	v_cndmask_b32_e64 v52, v177, v52, s[16:17]
	v_mfma_f32_16x16x32_bf16 v[46:49], v[22:25], v[122:125], v[18:21]
	ds_read_b128 v[22:25], v70 offset:18496
	v_cndmask_b32_e64 v53, v177, v53, s[18:19]
	s_nop 0
	ds_read_b128 v[18:21], v70 offset:18432
	s_waitcnt lgkmcnt(0)
	v_mfma_f32_16x16x32_bf16 v[18:21], v[18:21], v[82:85], 0
	s_nop 1
	v_cndmask_b32_e64 v46, v177, v46, s[20:21]
	v_cndmask_b32_e64 v47, v177, v47, s[22:23]
	v_cndmask_b32_e64 v48, v177, v48, s[24:25]
	v_mfma_f32_16x16x32_bf16 v[42:45], v[22:25], v[122:125], v[18:21]
	ds_read_b128 v[22:25], v71 offset:18496
	v_cndmask_b32_e64 v49, v177, v49, s[26:27]
	s_nop 0
	ds_read_b128 v[18:21], v71 offset:18432
	s_waitcnt lgkmcnt(0)
	v_mfma_f32_16x16x32_bf16 v[18:21], v[18:21], v[82:85], 0
	s_nop 1
	v_cndmask_b32_e64 v42, v177, v42, s[28:29]
	v_cndmask_b32_e64 v43, v177, v43, s[30:31]
	v_cndmask_b32_e64 v44, v177, v44, s[34:35]
	v_mfma_f32_16x16x32_bf16 v[38:41], v[22:25], v[122:125], v[18:21]
	ds_read_b128 v[22:25], v72 offset:18496
	v_cndmask_b32_e64 v45, v177, v45, s[36:37]
	s_nop 0
	ds_read_b128 v[18:21], v72 offset:18432
	s_waitcnt lgkmcnt(0)
	v_mfma_f32_16x16x32_bf16 v[18:21], v[18:21], v[82:85], 0
	s_nop 1
	v_cndmask_b32_e64 v38, v177, v38, s[38:39]
	v_cndmask_b32_e64 v39, v177, v39, s[40:41]
	v_cndmask_b32_e64 v40, v177, v40, s[42:43]
	v_mfma_f32_16x16x32_bf16 v[34:37], v[22:25], v[122:125], v[18:21]
	ds_read_b128 v[22:25], v73 offset:18496
	v_cndmask_b32_e64 v41, v177, v41, s[44:45]
	s_nop 0
	ds_read_b128 v[18:21], v73 offset:18432
	s_waitcnt lgkmcnt(0)
	v_mfma_f32_16x16x32_bf16 v[18:21], v[18:21], v[82:85], 0
	s_nop 1
	v_cndmask_b32_e64 v34, v177, v34, s[46:47]
	v_cndmask_b32_e64 v35, v177, v35, s[48:49]
	v_cndmask_b32_e64 v36, v177, v36, s[50:51]
	v_mfma_f32_16x16x32_bf16 v[30:33], v[22:25], v[122:125], v[18:21]
	ds_read_b128 v[22:25], v76 offset:18496
	v_cndmask_b32_e64 v37, v177, v37, s[52:53]
	s_nop 0
	ds_read_b128 v[18:21], v76 offset:18432
	s_waitcnt lgkmcnt(0)
	v_mfma_f32_16x16x32_bf16 v[18:21], v[18:21], v[82:85], 0
	s_nop 1
	v_cndmask_b32_e64 v30, v177, v30, s[54:55]
	v_cndmask_b32_e64 v31, v177, v31, s[56:57]
	v_cndmask_b32_e64 v32, v177, v32, s[58:59]
	v_mfma_f32_16x16x32_bf16 v[26:29], v[22:25], v[122:125], v[18:21]
	ds_read_b128 v[22:25], v77 offset:18496
	v_cndmask_b32_e64 v33, v177, v33, s[60:61]
	s_nop 0
	ds_read_b128 v[18:21], v77 offset:18432
	s_waitcnt lgkmcnt(0)
	v_mfma_f32_16x16x32_bf16 v[18:21], v[18:21], v[82:85], 0
	s_nop 1
	v_cndmask_b32_e64 v26, v177, v26, s[62:63]
	v_cndmask_b32_e64 v27, v177, v27, s[64:65]
	v_cndmask_b32_e64 v28, v177, v28, s[66:67]
	v_mfma_f32_16x16x32_bf16 v[22:25], v[22:25], v[122:125], v[18:21]
	v_cndmask_b32_e64 v29, v177, v29, s[68:69]
	s_nop 1
	ds_read_b128 v[18:21], v78 offset:18432
	s_waitcnt lgkmcnt(0)
	v_mfma_f32_16x16x32_bf16 v[18:21], v[18:21], v[82:85], 0
	ds_read_b128 v[82:85], v78 offset:18496
	s_nop 0
	v_cndmask_b32_e64 v22, v177, v22, s[70:71]
	v_cndmask_b32_e64 v23, v177, v23, s[72:73]
	s_waitcnt lgkmcnt(0)
	v_mfma_f32_16x16x32_bf16 v[18:21], v[82:85], v[122:125], v[18:21]
	s_waitcnt lgkmcnt(0)
	v_mov_b32_e32 v81, s99
	v_max3_f32 v82, v81, v54, v55
	v_max3_f32 v82, v82, v56, v57
	v_max3_f32 v82, v82, v50, v51
	v_max3_f32 v82, v82, v52, v53
	v_max3_f32 v82, v82, v46, v47
	v_max3_f32 v82, v82, v48, v49
	v_max3_f32 v82, v82, v42, v43
	v_max3_f32 v82, v82, v44, v45
	v_max3_f32 v82, v82, v38, v39
	v_max3_f32 v82, v82, v40, v41
	v_max3_f32 v82, v82, v34, v35
	v_max3_f32 v82, v82, v36, v37
	v_max3_f32 v82, v82, v30, v31
	v_max3_f32 v82, v82, v32, v33
	v_max3_f32 v82, v82, v26, v27
	v_max3_f32 v82, v82, v28, v29
	v_max3_f32 v82, v82, v22, v23
	v_cndmask_b32_e64 v24, v177, v24, s[74:75]
	v_cndmask_b32_e64 v25, v177, v25, s[76:77]
	v_max3_f32 v82, v82, v24, v25
	v_cndmask_b32_e64 v83, v177, v18, s[78:79]
	v_cndmask_b32_e64 v19, v177, v19, s[80:81]
	v_max3_f32 v18, v82, v83, v19
	v_cndmask_b32_e64 v82, v177, v20, s[82:83]
	v_cndmask_b32_e64 v84, v177, v21, s[84:85]
	v_max3_f32 v18, v18, v82, v84
	ds_bpermute_b32 v20, v74, v18
	s_waitcnt lgkmcnt(0)
	v_max_f32_e32 v20, v20, v20
	v_max_f32_e32 v18, v18, v20
	ds_bpermute_b32 v20, v75, v18
	s_waitcnt lgkmcnt(0)
; __device__ __forceinline__ unsigned cvt_pk_bf16(float lo, float hi) { unsigned r; asm volatile("v_cvt_pk_bf16_f32 %0, %1, %2" : "=v"(r) : "v"(lo), "v"(hi)); return r; }
; #define LAS __attribute__((address_space(3)))
; __device__ __forceinline__ void swa_compute(SwaRaw& R, int b, int kvh, int nb, const bf16_t* P, const float* __restrict__ qg, const float* __restrict__ kg, const float* __restrict__ sinks, bf16_t* OB, LAS unsigned char* lds, int tid) {
;     ...
;         float sum = 0.f;
; #pragma unroll
;         for (int j = 0; j < 10; ++j) {
; #pragma unroll
;             for (int r = 0; r < 4; ++r) { s[j][r] = __expf(s[j][r] - m); sum += s[j][r]; }
;             u32x2 w; w.x = cvt_pk_bf16(s[j][0], s[j][1]); w.y = cvt_pk_bf16(s[j][2], s[j][3]);
;             *(LAS u32x2*)(Pw + fr * 168 + j * 16 + 4 * fq) = w; }
;         sum += __shfl_xor(sum, 16); sum += __shfl_xor(sum, 32);
	v_max_f32_e32 v20, v20, v20
	v_max_f32_e32 v18, v18, v20
	v_sub_f32_e32 v20, v54, v18
	v_mul_f32_e32 v20, 0x3fb8aa3b, v20
	v_sub_f32_e32 v54, v55, v18
	v_exp_f32_e32 v20, v20
	v_mul_f32_e32 v54, 0x3fb8aa3b, v54
	v_sub_f32_e32 v55, v56, v18
	v_exp_f32_e32 v54, v54
	v_mul_f32_e32 v55, 0x3fb8aa3b, v55
	v_sub_f32_e32 v56, v57, v18
	v_exp_f32_e32 v55, v55
	v_mul_f32_e32 v56, 0x3fb8aa3b, v56
	v_exp_f32_e32 v56, v56
	v_add_f32_e32 v21, 0, v20
	v_add_f32_e32 v21, v54, v21
	v_add_f32_e32 v21, v55, v21
	v_cvt_pk_bf16_f32 v20, v20, v54
	v_add_f32_e32 v57, v56, v21
	v_cvt_pk_bf16_f32 v21, v55, v56
	ds_write_b64 v65, v[20:21]
	v_sub_f32_e32 v20, v50, v18
	v_mul_f32_e32 v20, 0x3fb8aa3b, v20
	v_sub_f32_e32 v50, v51, v18
	v_exp_f32_e32 v20, v20
	v_mul_f32_e32 v50, 0x3fb8aa3b, v50
	v_sub_f32_e32 v51, v52, v18
	v_exp_f32_e32 v50, v50
	v_mul_f32_e32 v51, 0x3fb8aa3b, v51
	v_sub_f32_e32 v52, v53, v18
	v_exp_f32_e32 v51, v51
	v_mul_f32_e32 v52, 0x3fb8aa3b, v52
	v_exp_f32_e32 v52, v52
	v_add_f32_e32 v21, v20, v57
	v_add_f32_e32 v21, v50, v21
	v_add_f32_e32 v21, v51, v21
	v_cvt_pk_bf16_f32 v20, v20, v50
	v_add_f32_e32 v53, v52, v21
	v_cvt_pk_bf16_f32 v21, v51, v52
	ds_write_b64 v65, v[20:21] offset:32
	v_sub_f32_e32 v20, v46, v18
	v_mul_f32_e32 v20, 0x3fb8aa3b, v20
	v_sub_f32_e32 v46, v47, v18
	v_exp_f32_e32 v20, v20
	v_mul_f32_e32 v46, 0x3fb8aa3b, v46
	v_sub_f32_e32 v47, v48, v18
	v_exp_f32_e32 v46, v46
	v_mul_f32_e32 v47, 0x3fb8aa3b, v47
	v_sub_f32_e32 v48, v49, v18
	v_exp_f32_e32 v47, v47
	v_mul_f32_e32 v48, 0x3fb8aa3b, v48
	v_exp_f32_e32 v48, v48
	v_add_f32_e32 v21, v20, v53
	v_add_f32_e32 v21, v46, v21
	v_add_f32_e32 v21, v47, v21
	v_cvt_pk_bf16_f32 v20, v20, v46
	v_add_f32_e32 v49, v48, v21
	v_cvt_pk_bf16_f32 v21, v47, v48
	ds_write_b64 v65, v[20:21] offset:64
	v_sub_f32_e32 v20, v42, v18
	v_mul_f32_e32 v20, 0x3fb8aa3b, v20
	v_sub_f32_e32 v42, v43, v18
	v_exp_f32_e32 v20, v20
	v_mul_f32_e32 v42, 0x3fb8aa3b, v42
	v_sub_f32_e32 v43, v44, v18
	v_exp_f32_e32 v42, v42
	v_mul_f32_e32 v43, 0x3fb8aa3b, v43
	v_sub_f32_e32 v44, v45, v18
	v_exp_f32_e32 v43, v43
	v_mul_f32_e32 v44, 0x3fb8aa3b, v44
	v_exp_f32_e32 v44, v44
	v_add_f32_e32 v21, v20, v49
	v_add_f32_e32 v21, v42, v21
	v_add_f32_e32 v21, v43, v21
	v_cvt_pk_bf16_f32 v20, v20, v42
	v_add_f32_e32 v45, v44, v21
	v_cvt_pk_bf16_f32 v21, v43, v44
	ds_write_b64 v65, v[20:21] offset:96
	v_sub_f32_e32 v20, v38, v18
	v_mul_f32_e32 v20, 0x3fb8aa3b, v20
	v_sub_f32_e32 v38, v39, v18
	v_exp_f32_e32 v20, v20
	v_mul_f32_e32 v38, 0x3fb8aa3b, v38
	v_sub_f32_e32 v39, v40, v18
	v_exp_f32_e32 v38, v38
	v_mul_f32_e32 v39, 0x3fb8aa3b, v39
	v_sub_f32_e32 v40, v41, v18
	v_exp_f32_e32 v39, v39
	v_mul_f32_e32 v40, 0x3fb8aa3b, v40
	v_exp_f32_e32 v40, v40
	v_add_f32_e32 v21, v20, v45
	v_add_f32_e32 v21, v38, v21
	v_add_f32_e32 v21, v39, v21
	v_cvt_pk_bf16_f32 v20, v20, v38
	v_add_f32_e32 v41, v40, v21
	v_cvt_pk_bf16_f32 v21, v39, v40
	ds_write_b64 v65, v[20:21] offset:128
	v_sub_f32_e32 v20, v34, v18
	v_mul_f32_e32 v20, 0x3fb8aa3b, v20
	v_sub_f32_e32 v34, v35, v18
	v_exp_f32_e32 v20, v20
	v_mul_f32_e32 v34, 0x3fb8aa3b, v34
	v_sub_f32_e32 v35, v36, v18
	v_exp_f32_e32 v34, v34
	v_mul_f32_e32 v35, 0x3fb8aa3b, v35
	v_sub_f32_e32 v36, v37, v18
	v_exp_f32_e32 v35, v35
	v_mul_f32_e32 v36, 0x3fb8aa3b, v36
	v_exp_f32_e32 v36, v36
	v_add_f32_e32 v21, v20, v41
	v_add_f32_e32 v21, v34, v21
	v_add_f32_e32 v21, v35, v21
	v_cvt_pk_bf16_f32 v20, v20, v34
	v_add_f32_e32 v37, v36, v21
	v_cvt_pk_bf16_f32 v21, v35, v36
	ds_write_b64 v65, v[20:21] offset:160
	v_sub_f32_e32 v20, v30, v18
	v_mul_f32_e32 v20, 0x3fb8aa3b, v20
	v_sub_f32_e32 v30, v31, v18
	v_exp_f32_e32 v20, v20
	v_mul_f32_e32 v30, 0x3fb8aa3b, v30
	v_sub_f32_e32 v31, v32, v18
	v_exp_f32_e32 v30, v30
	v_mul_f32_e32 v31, 0x3fb8aa3b, v31
	v_sub_f32_e32 v32, v33, v18
	v_exp_f32_e32 v31, v31
	v_mul_f32_e32 v32, 0x3fb8aa3b, v32
	v_exp_f32_e32 v32, v32
	v_add_f32_e32 v21, v20, v37
	v_add_f32_e32 v21, v30, v21
	v_add_f32_e32 v21, v31, v21
	v_cvt_pk_bf16_f32 v20, v20, v30
	v_add_f32_e32 v33, v32, v21
	v_cvt_pk_bf16_f32 v21, v31, v32
	ds_write_b64 v65, v[20:21] offset:192
	v_sub_f32_e32 v20, v26, v18
	v_mul_f32_e32 v20, 0x3fb8aa3b, v20
	v_sub_f32_e32 v26, v27, v18
	v_exp_f32_e32 v20, v20
	v_mul_f32_e32 v26, 0x3fb8aa3b, v26
	v_sub_f32_e32 v27, v28, v18
	v_exp_f32_e32 v26, v26
	v_mul_f32_e32 v27, 0x3fb8aa3b, v27
	v_sub_f32_e32 v28, v29, v18
	v_exp_f32_e32 v27, v27
	v_mul_f32_e32 v28, 0x3fb8aa3b, v28
	v_exp_f32_e32 v28, v28
	v_add_f32_e32 v21, v20, v33
	v_add_f32_e32 v21, v26, v21
	v_add_f32_e32 v21, v27, v21
	v_cvt_pk_bf16_f32 v20, v20, v26
	v_add_f32_e32 v29, v28, v21
	v_cvt_pk_bf16_f32 v21, v27, v28
	ds_write_b64 v65, v[20:21] offset:224
	v_sub_f32_e32 v20, v22, v18
	v_mul_f32_e32 v20, 0x3fb8aa3b, v20
	v_sub_f32_e32 v22, v23, v18
	v_exp_f32_e32 v20, v20
	v_mul_f32_e32 v22, 0x3fb8aa3b, v22
	v_sub_f32_e32 v23, v24, v18
	v_exp_f32_e32 v22, v22
	v_mul_f32_e32 v23, 0x3fb8aa3b, v23
	v_sub_f32_e32 v24, v25, v18
	v_exp_f32_e32 v23, v23
	v_mul_f32_e32 v24, 0x3fb8aa3b, v24
	v_exp_f32_e32 v24, v24
	v_add_f32_e32 v21, v20, v29
	v_add_f32_e32 v21, v22, v21
	v_add_f32_e32 v21, v23, v21
	v_cvt_pk_bf16_f32 v20, v20, v22
	v_add_f32_e32 v25, v24, v21
	v_cvt_pk_bf16_f32 v21, v23, v24
	ds_write_b64 v65, v[20:21] offset:256
	v_sub_f32_e32 v20, v83, v18
	v_mul_f32_e32 v20, 0x3fb8aa3b, v20
	v_sub_f32_e32 v19, v19, v18
	v_exp_f32_e32 v20, v20
	v_mul_f32_e32 v19, 0x3fb8aa3b, v19
	v_sub_f32_e32 v22, v82, v18
	v_exp_f32_e32 v19, v19
	v_mul_f32_e32 v22, 0x3fb8aa3b, v22
	v_sub_f32_e32 v23, v84, v18
	v_exp_f32_e32 v22, v22
	v_mul_f32_e32 v23, 0x3fb8aa3b, v23
	v_exp_f32_e32 v23, v23
	v_add_f32_e32 v21, v20, v25
	v_add_f32_e32 v21, v19, v21
	v_add_f32_e32 v21, v22, v21
	v_add_f32_e32 v24, v23, v21
	v_cvt_pk_bf16_f32 v20, v20, v19
	ds_bpermute_b32 v19, v74, v24
	v_cvt_pk_bf16_f32 v21, v22, v23
	ds_write_b64 v65, v[20:21] offset:288
	v_sub_f32_e32 v18, v81, v18
	v_mul_f32_e32 v18, 0x3fb8aa3b, v18
	s_waitcnt lgkmcnt(1)
; __device__ __forceinline__ unsigned cvt_pk_bf16(float lo, float hi) { unsigned r; asm volatile("v_cvt_pk_bf16_f32 %0, %1, %2" : "=v"(r) : "v"(lo), "v"(hi)); return r; }
; #define LAS __attribute__((address_space(3)))
; #define MFMA16(a, b, c) __builtin_amdgcn_mfma_f32_16x16x32_bf16((a), (b), (c), 0, 0, 0)
; __device__ __forceinline__ void swa_compute(SwaRaw& R, int b, int kvh, int nb, const bf16_t* P, const float* __restrict__ qg, const float* __restrict__ kg, const float* __restrict__ sinks, bf16_t* OB, LAS unsigned char* lds, int tid) {
;     ...
;         const float inv = 1.0f / (sum + __expf(sink - m));
;         asm volatile("s_waitcnt lgkmcnt(0)" ::: "memory"); __builtin_amdgcn_wave_barrier();
; #pragma unroll
;         for (int dt = 0; dt < 4; ++dt) { f32x4 acc = {0.f, 0.f, 0.f, 0.f};
; #pragma unroll
;             for (int ks = 0; ks < 5; ++ks) { const LAS bf16_t* vp = Vr + (kt0 * 16 + ks * 32 + 8 * fq + (fr >> 2)) * 72 + dt * 16 + 4 * (fr & 3);
;                 const v4i16_t lo = __builtin_amdgcn_ds_read_tr16_b64_v4i16((LAS v4i16_t*)vp), hi = __builtin_amdgcn_ds_read_tr16_b64_v4i16((LAS v4i16_t*)(vp + 4 * 72));
;                 const bf16x8 vf = {lo[0], lo[1], lo[2], lo[3], hi[0], hi[1], hi[2], hi[3]};
;                 acc = MFMA16(vf, ldfrag(Pw, 168, fr, ks * 32 + 8 * fq), acc); }
;             u32x2 w; w.x = cvt_pk_bf16(acc[0] * inv, acc[1] * inv); w.y = cvt_pk_bf16(acc[2] * inv, acc[3] * inv);
;             *(u32x2*)(OB + (rq0 + qi) * 1024 + hq * 64 + dt * 16 + 4 * fq) = w; }
	v_add_f32_e32 v19, v24, v19
	ds_bpermute_b32 v20, v75, v19
	v_exp_f32_e32 v18, v18
	v_add_u32_e32 v33, v165, v66
	v_add_u32_e32 v34, v65, v94
	s_waitcnt lgkmcnt(0)
	s_waitcnt lgkmcnt(0)
	v_add_f32_e32 v19, v19, v20
	v_add_f32_e32 v18, v18, v19
	v_div_scale_f32 v19, s[88:89], v18, v18, 1.0
	v_rcp_f32_e32 v20, v19
	s_nop 0
	v_fma_f32 v21, -v19, v20, 1.0
	v_fmac_f32_e32 v20, v21, v20
	v_div_scale_f32 v21, vcc, 1.0, v18, 1.0
	v_mul_f32_e32 v22, v21, v20
	v_fma_f32 v23, -v19, v22, v21
	v_fmac_f32_e32 v22, v23, v20
	v_fma_f32 v19, -v19, v22, v21
	v_div_fmas_f32 v19, v19, v20, v22
	ds_read_b64_tr_b16 v[192:193], v33 offset:55296
	ds_read_b64_tr_b16 v[194:195], v33 offset:55872
	ds_read_b128 v[24:27], v34
	ds_read_b64_tr_b16 v[196:197], v33 offset:59904
	ds_read_b64_tr_b16 v[198:199], v33 offset:60480
	ds_read_b128 v[28:31], v34 offset:64
	ds_read_b64_tr_b16 v[200:201], v33 offset:64512
	ds_read_b64_tr_b16 v[202:203], v33 offset:65088
	ds_read_b128 v[212:215], v34 offset:128
	ds_read_b64_tr_b16 v[204:205], v79 offset:55296
	ds_read_b64_tr_b16 v[206:207], v79 offset:55872
	ds_read_b64_tr_b16 v[208:209], v80 offset:55296
	ds_read_b64_tr_b16 v[210:211], v80 offset:55872
	s_waitcnt lgkmcnt(10)
	v_mfma_f32_16x16x32_bf16 v[20:23], v[192:195], v[24:27], 0
	ds_read_b128 v[24:27], v34 offset:192
	ds_read_b64_tr_b16 v[192:193], v33 offset:55328
	ds_read_b64_tr_b16 v[194:195], v33 offset:55904
	v_div_fixup_f32 v32, v19, v18, 1.0
	v_lshl_add_u64 v[18:19], v[60:61], 0, s[86:87]
	s_waitcnt lgkmcnt(10)
	v_mfma_f32_16x16x32_bf16 v[20:23], v[196:199], v[28:31], v[20:23]
	ds_read_b128 v[28:31], v34 offset:256
	ds_read_b64_tr_b16 v[196:197], v33 offset:59936
	ds_read_b64_tr_b16 v[198:199], v33 offset:60512
	s_add_u32 s86, s86, 0x80
	s_addc_u32 s87, s87, 0
	s_waitcnt lgkmcnt(10)
	v_mfma_f32_16x16x32_bf16 v[20:23], v[200:203], v[212:215], v[20:23]
	ds_read_b128 v[212:215], v34
	ds_read_b64_tr_b16 v[200:201], v33 offset:64544
	ds_read_b64_tr_b16 v[202:203], v33 offset:65120
	s_add_u32 s2, s2, 4
	s_addc_u32 s3, s3, 0
	s_waitcnt lgkmcnt(8)
	v_mfma_f32_16x16x32_bf16 v[20:23], v[204:207], v[24:27], v[20:23]
	ds_read_b128 v[24:27], v34 offset:64
	ds_read_b64_tr_b16 v[204:205], v79 offset:55328
	ds_read_b64_tr_b16 v[206:207], v79 offset:55904
	s_cmpk_lg_i32 s86, 0x200
	s_waitcnt lgkmcnt(8)
	v_mfma_f32_16x16x32_bf16 v[20:23], v[208:211], v[28:31], v[20:23]
	ds_read_b128 v[28:31], v34 offset:128
	ds_read_b64_tr_b16 v[208:209], v80 offset:55328
	ds_read_b64_tr_b16 v[210:211], v80 offset:55904
	s_nop 7
	v_mul_f32_e32 v20, v20, v32
	v_mul_f32_e32 v21, v21, v32
	v_cvt_pk_bf16_f32 v20, v20, v21
	v_mul_f32_e32 v21, v22, v32
	v_mul_f32_e32 v22, v23, v32
	v_cvt_pk_bf16_f32 v21, v21, v22
	global_store_dwordx2 v[18:19], v[20:21], off offset:-64
	s_waitcnt lgkmcnt(8)
	v_mfma_f32_16x16x32_bf16 v[20:23], v[192:195], v[212:215], 0
	ds_read_b128 v[212:215], v34 offset:192
	ds_read_b64_tr_b16 v[192:193], v33 offset:55360
	ds_read_b64_tr_b16 v[194:195], v33 offset:55936
	s_waitcnt lgkmcnt(8)
	v_mfma_f32_16x16x32_bf16 v[20:23], v[196:199], v[24:27], v[20:23]
	ds_read_b128 v[24:27], v34 offset:256
	ds_read_b64_tr_b16 v[196:197], v33 offset:59968
	ds_read_b64_tr_b16 v[198:199], v33 offset:60544
	s_waitcnt lgkmcnt(8)
	v_mfma_f32_16x16x32_bf16 v[20:23], v[200:203], v[28:31], v[20:23]
	ds_read_b128 v[28:31], v34
	ds_read_b64_tr_b16 v[200:201], v33 offset:64576
	ds_read_b64_tr_b16 v[202:203], v33 offset:65152
	s_waitcnt lgkmcnt(8)
	v_mfma_f32_16x16x32_bf16 v[20:23], v[204:207], v[212:215], v[20:23]
	ds_read_b128 v[212:215], v34 offset:64
	ds_read_b64_tr_b16 v[204:205], v79 offset:55360
	ds_read_b64_tr_b16 v[206:207], v79 offset:55936
	s_waitcnt lgkmcnt(8)
	v_mfma_f32_16x16x32_bf16 v[20:23], v[208:211], v[24:27], v[20:23]
	ds_read_b128 v[24:27], v34 offset:128
	ds_read_b64_tr_b16 v[208:209], v80 offset:55360
	ds_read_b64_tr_b16 v[210:211], v80 offset:55936
	s_nop 7
	v_mul_f32_e32 v20, v20, v32
	v_mul_f32_e32 v21, v21, v32
	v_cvt_pk_bf16_f32 v20, v20, v21
	v_mul_f32_e32 v21, v22, v32
	v_mul_f32_e32 v22, v23, v32
	v_cvt_pk_bf16_f32 v21, v21, v22
	global_store_dwordx2 v[18:19], v[20:21], off offset:-32
	s_waitcnt lgkmcnt(8)
	v_mfma_f32_16x16x32_bf16 v[20:23], v[192:195], v[28:31], 0
	ds_read_b128 v[28:31], v34 offset:192
	ds_read_b64_tr_b16 v[192:193], v33 offset:55392
	ds_read_b64_tr_b16 v[194:195], v33 offset:55968
	s_waitcnt lgkmcnt(8)
	v_mfma_f32_16x16x32_bf16 v[20:23], v[196:199], v[212:215], v[20:23]
	ds_read_b128 v[212:215], v34 offset:256
	ds_read_b64_tr_b16 v[196:197], v33 offset:60000
	ds_read_b64_tr_b16 v[198:199], v33 offset:60576
	s_waitcnt lgkmcnt(8)
	v_mfma_f32_16x16x32_bf16 v[20:23], v[200:203], v[24:27], v[20:23]
	ds_read_b128 v[24:27], v34
	ds_read_b64_tr_b16 v[200:201], v33 offset:64608
	ds_read_b64_tr_b16 v[202:203], v33 offset:65184
	s_waitcnt lgkmcnt(8)
	v_mfma_f32_16x16x32_bf16 v[20:23], v[204:207], v[28:31], v[20:23]
	ds_read_b128 v[28:31], v34 offset:64
	ds_read_b64_tr_b16 v[204:205], v79 offset:55392
	ds_read_b64_tr_b16 v[206:207], v79 offset:55968
	s_waitcnt lgkmcnt(8)
	v_mfma_f32_16x16x32_bf16 v[20:23], v[208:211], v[212:215], v[20:23]
	ds_read_b128 v[212:215], v34 offset:128
	ds_read_b64_tr_b16 v[208:209], v80 offset:55392
	ds_read_b64_tr_b16 v[210:211], v80 offset:55968
	s_nop 7
	v_mul_f32_e32 v20, v32, v20
	v_mul_f32_e32 v21, v32, v21
	v_cvt_pk_bf16_f32 v20, v20, v21
	v_mul_f32_e32 v21, v32, v22
	v_mul_f32_e32 v22, v32, v23
	v_cvt_pk_bf16_f32 v21, v21, v22
	global_store_dwordx2 v[18:19], v[20:21], off
	s_waitcnt lgkmcnt(8)
	v_mfma_f32_16x16x32_bf16 v[20:23], v[192:195], v[24:27], 0
	ds_read_b128 v[24:27], v34 offset:192
	s_waitcnt lgkmcnt(6)
	v_mfma_f32_16x16x32_bf16 v[20:23], v[196:199], v[28:31], v[20:23]
	ds_read_b128 v[28:31], v34 offset:256
	s_waitcnt lgkmcnt(4)
	v_mfma_f32_16x16x32_bf16 v[20:23], v[200:203], v[212:215], v[20:23]
	s_waitcnt lgkmcnt(1)
	v_mfma_f32_16x16x32_bf16 v[20:23], v[204:207], v[24:27], v[20:23]
	s_waitcnt lgkmcnt(0)
	v_mfma_f32_16x16x32_bf16 v[20:23], v[208:211], v[28:31], v[20:23]
	s_nop 7
	v_mul_f32_e32 v20, v32, v20
	v_mul_f32_e32 v21, v32, v21
	v_cvt_pk_bf16_f32 v20, v20, v21
	v_mul_f32_e32 v21, v32, v22
	v_mul_f32_e32 v22, v32, v23
	v_cvt_pk_bf16_f32 v21, v21, v22
	global_store_dwordx2 v[18:19], v[20:21], off offset:32
	s_waitcnt lgkmcnt(0)
	s_barrier
	s_cbranch_scc0 .LBB0_473
